# m14 + stick loop: next-tile K/V prefetch issued after the Q loads for active waves (vmcnt order fix)
# baseline (speedup 1.0000x reference)
; #define LAS __attribute__((address_space(3)))
; #define FA_SLOAD(jj) do { const size_t k0_ = (size_t)(jj) * 64; vs0 = *(const bf16x8*)(Vb + (k0_ + sr) * ldk + sc); vs1 = *(const bf16x8*)(Vb + (k0_ + 32 + sr) * ldk + sc); \
;         ks0 = *(const bf16x8*)(Kb + (k0_ + sr) * ldk + sc); ks1 = *(const bf16x8*)(Kb + (k0_ + 32 + sr) * ldk + sc); } while (0)
; #define FA_SWRITE(b) do { *(LAS bf16x8*)(V_lds + (b) * SHM_V + vst0) = vs0; *(LAS bf16x8*)(V_lds + (b) * SHM_V + vst1) = vs1; \
;         *(LAS bf16x8*)(K_lds + (b) * SHM_K + kst0) = ks0; *(LAS bf16x8*)(K_lds + (b) * SHM_K + kst1) = ks1; } while (0)
; template <int MODE>
; DEVI void attn_unit(LAS unsigned char* lds, const bf16_t* Qw, int ldq, const bf16_t* Kb, const bf16_t* Vb, int ldk, bf16_t* Ow, int ldo,
;                     int j_first, int ntiles, int jstep, int wj_lo, int wj_hi, int t0) {
;     ...
;     for (int i = 0; i < ntiles; ++i, j += jstep) {
;         const int buf = i & 1;
;         FA_SWRITE(buf);
;         asm volatile("" ::: "memory");
;         if (i + 1 < ntiles) FA_SLOAD(j + jstep);
;         asm volatile("s_waitcnt lgkmcnt(0)" ::: "memory"); __builtin_amdgcn_s_barrier(); asm volatile("" ::: "memory");
;         if constexpr (MODE == M_STICK) {
;             if (i > 0) { const u32x4 f0 = *(LAS const u32x4*)(dflag + ((i - 1) & 1) * 8), f1 = *(LAS const u32x4*)(dflag + ((i - 1) & 1) * 8 + 4);
;                 if ((f0.x & f0.y & f0.z & f0.w & f1.x & f1.y & f1.z & f1.w) != 0u) break; }
;             if (lane == 0) dflag[(i & 1) * 8 + wid] = mydone ? 1u : 0u;
;         }
;         if (j >= wj_lo && j <= wj_hi && !mydone) {
.LBB11_992:
	s_add_i32 s1, s36, -1
	s_and_b32 s25, s1, 1
	s_lshl_b32 s1, s25, 14
	v_add_u32_e32 v2, s1, v160
	v_add3_u32 v68, v2, v161, v158
	v_add3_u32 v2, v2, v162, v158
	s_add_i32 s6, s1, 0
	s_waitcnt vmcnt(3)
	ds_write_b128 v68, v[100:103]
	s_waitcnt vmcnt(2)
	ds_write_b128 v2, v[104:107]
	v_add3_u32 v2, s6, v156, v159
	s_waitcnt vmcnt(1)
	ds_write_b128 v2, v[108:111] offset:32768
	v_add3_u32 v2, s6, v157, v159
	s_waitcnt vmcnt(0)
	ds_write_b128 v2, v[112:115] offset:32768
	s_cmp_ge_u32 s36, s29
	s_cbranch_scc1 .LBB11_994
	s_add_i32 s101, s22, -1
	v_cmp_gt_i32_e32 vcc, s101, v178
	s_cmp_lt_i32 s22, 1
	s_cselect_b64 s[4:5], -1, 0
	s_or_b64 s[4:5], s[4:5], vcc
	s_or_b64 s[4:5], s[4:5], s[14:15]
	s_and_b64 vcc, exec, s[4:5]
	s_cbranch_vccz .LBB11_994
	v_lshl_add_u64 v[68:69], v[140:141], 0, s[30:31]
	v_add_co_u32_e32 v70, vcc, 0x532c2000, v68
	s_nop 1
	v_addc_co_u32_e32 v71, vcc, 0, v69, vcc
	v_add_co_u32_e32 v72, vcc, 0x53322000, v68
	s_nop 1
	v_addc_co_u32_e32 v73, vcc, 0, v69, vcc
	global_load_dwordx4 v[100:103], v[70:71], off
	global_load_dwordx4 v[104:107], v[72:73], off
	v_add_co_u32_e32 v70, vcc, 0x532c1000, v68
	s_nop 1
	v_addc_co_u32_e32 v71, vcc, 0, v69, vcc
	v_add_co_u32_e32 v68, vcc, 0x53321000, v68
	s_nop 1
	v_addc_co_u32_e32 v69, vcc, 0, v69, vcc
	global_load_dwordx4 v[108:111], v[70:71], off
	global_load_dwordx4 v[112:115], v[68:69], off

; #define LAS __attribute__((address_space(3)))
; DEVI void qkt(f32x16& p0, f32x16& p1, LAS const unsigned char* Ks, const bf16x8* qr, int r32, int hi) {
;     p0 = (f32x16){0.f, 0.f, 0.f, 0.f, 0.f, 0.f, 0.f, 0.f, 0.f, 0.f, 0.f, 0.f, 0.f, 0.f, 0.f, 0.f}; p1 = p0;
; #pragma unroll
;     for (int d0 = 0; d0 < 8; ++d0) { const int cb = (d0 * 16 + hi * 8) * 2;
;         const bf16x8 b0 = *(LAS const bf16x8*)(Ks + FA_KSWZ(r32, cb));
;         const bf16x8 b1 = *(LAS const bf16x8*)(Ks + FA_KSWZ(32 + r32, cb));
;         p0 = __builtin_amdgcn_mfma_f32_32x32x16_bf16(b0, qr[d0], p0, 0, 0, 0);
;         p1 = __builtin_amdgcn_mfma_f32_32x32x16_bf16(b1, qr[d0], p1, 0, 0, 0); }
; template <int MODE>
; DEVI void attn_unit(LAS unsigned char* lds, const bf16_t* Qw, int ldq, const bf16_t* Kb, const bf16_t* Vb, int ldk, bf16_t* Ow, int ldo,
;                     int j_first, int ntiles, int jstep, int wj_lo, int wj_hi, int t0) {
;     ...
;         if (i + 1 < ntiles) FA_SLOAD(j + jstep);
;         asm volatile("s_waitcnt lgkmcnt(0)" ::: "memory"); __builtin_amdgcn_s_barrier(); asm volatile("" ::: "memory");
;         if constexpr (MODE == M_STICK) {
;             if (i > 0) { const u32x4 f0 = *(LAS const u32x4*)(dflag + ((i - 1) & 1) * 8), f1 = *(LAS const u32x4*)(dflag + ((i - 1) & 1) * 8 + 4);
;                 if ((f0.x & f0.y & f0.z & f0.w & f1.x & f1.y & f1.z & f1.w) != 0u) break; }
;             if (lane == 0) dflag[(i & 1) * 8 + wid] = mydone ? 1u : 0u;
;         }
;         if (j >= wj_lo && j <= wj_hi && !mydone) {
;             f32x16 p0, p1;
;             if constexpr (MODE == M_STICK) {
;                 int qz_ = 0; asm volatile("" : "+v"(qz_)); const bf16_t* qp2 = qp + qz_;
; #pragma unroll
;                 for (int d0 = 0; d0 < 8; ++d0) qr[d0] = *(const bf16x8*)(qp2 + d0 * 16); }
;             qkt(p0, p1, K_lds + buf * SHM_K, qr, r32, hi);
;             bf16x8 pa0, pa1, pa2, pa3;
;             if constexpr (MODE == M_STICK) {
;                 const int tq = t0 + r32; const bool diag = (64 * j + 63 >= t0);
;                 stick_half(p1, carry, diag, 64 * j + 32 + 4 * hi, tq, hi);
;                 stick_half(p0, carry, diag, 64 * j + 4 * hi, tq, hi);
.LBB11_996:
	s_and_saveexec_b64 s[4:5], s[40:41]
	v_lshl_add_u32 v2, s25, 5, v163
	v_cndmask_b32_e64 v68, 0, 1, s[14:15]
	ds_write_b32 v2, v68
	s_or_b64 exec, exec, s[4:5]
	s_add_i32 s37, s22, -1
	s_cmp_lt_i32 s22, 1
	s_cselect_b64 s[4:5], -1, 0
	v_cmp_gt_i32_e32 vcc, s37, v178
	s_or_b64 s[4:5], s[4:5], vcc
	s_nor_b64 s[4:5], s[4:5], s[14:15]
	s_and_saveexec_b64 s[20:21], s[4:5]
	s_cbranch_execz .LBB11_1002
	v_mov_b32_e32 v68, 0
	v_add_u32_e32 v2, s6, v167
	v_ashrrev_i32_e32 v69, 31, v68
	v_lshl_add_u64 v[154:155], v[68:69], 1, v[134:135]
	global_load_dwordx4 v[84:87], v[154:155], off
	global_load_dwordx4 v[142:145], v[154:155], off offset:32
	v_add_u32_e32 v72, v2, v168
	ds_read_b128 v[68:71], v72 offset:32768
	ds_read_b128 v[88:91], v72 offset:40960
	global_load_dwordx4 v[146:149], v[154:155], off offset:64
	v_add_u32_e32 v138, v2, v169
	ds_read_b128 v[150:153], v138 offset:32768
	ds_read_b128 v[198:201], v138 offset:40960
	v_add_u32_e32 v138, v2, v170
	s_add_i32 s4, s33, 63
	v_add_u32_e32 v224, s33, v176
	s_mov_b32 s12, 0xc3180000
	s_waitcnt vmcnt(2) lgkmcnt(3)
	v_mfma_f32_32x32x16_bf16 v[68:83], v[68:71], v[84:87], 0
	s_waitcnt vmcnt(1) lgkmcnt(1)
	v_mfma_f32_32x32x16_bf16 v[68:83], v[150:153], v[142:145], v[68:83]
	global_load_dwordx4 v[150:153], v[154:155], off offset:96
	v_mfma_f32_32x32x16_bf16 v[84:99], v[88:91], v[84:87], 0
	s_waitcnt lgkmcnt(0)
	v_mfma_f32_32x32x16_bf16 v[84:99], v[198:201], v[142:145], v[84:99]
	ds_read_b128 v[142:145], v138 offset:32768
	ds_read_b128 v[198:201], v138 offset:40960
	v_add_u32_e32 v138, v2, v171
	s_waitcnt vmcnt(1) lgkmcnt(1)
	v_mfma_f32_32x32x16_bf16 v[68:83], v[142:145], v[146:149], v[68:83]
	global_load_dwordx4 v[142:145], v[154:155], off offset:128
	s_waitcnt lgkmcnt(0)
	v_mfma_f32_32x32x16_bf16 v[84:99], v[198:201], v[146:149], v[84:99]
	ds_read_b128 v[146:149], v138 offset:32768
	ds_read_b128 v[198:201], v138 offset:40960
	v_add_u32_e32 v138, v2, v172
	s_waitcnt vmcnt(1) lgkmcnt(1)
	v_mfma_f32_32x32x16_bf16 v[68:83], v[146:149], v[150:153], v[68:83]
	global_load_dwordx4 v[146:149], v[154:155], off offset:160
	s_waitcnt lgkmcnt(0)
	v_mfma_f32_32x32x16_bf16 v[84:99], v[198:201], v[150:153], v[84:99]
	ds_read_b128 v[150:153], v138 offset:32768
	ds_read_b128 v[198:201], v138 offset:40960
	v_add_u32_e32 v138, v2, v173
	s_waitcnt vmcnt(1) lgkmcnt(1)
	v_mfma_f32_32x32x16_bf16 v[68:83], v[150:153], v[142:145], v[68:83]
	global_load_dwordx4 v[150:153], v[154:155], off offset:192
	s_waitcnt lgkmcnt(0)
	v_mfma_f32_32x32x16_bf16 v[84:99], v[198:201], v[142:145], v[84:99]
	ds_read_b128 v[142:145], v138 offset:32768
	ds_read_b128 v[198:201], v138 offset:40960
	v_add_u32_e32 v138, v2, v174
	v_add_u32_e32 v2, v2, v175
	s_waitcnt vmcnt(1) lgkmcnt(1)
	v_mfma_f32_32x32x16_bf16 v[68:83], v[142:145], v[146:149], v[68:83]
	global_load_dwordx4 v[142:145], v[154:155], off offset:224
	s_add_u32 vcc_lo, s30, 0x532c2000
	s_addc_u32 vcc_hi, s31, 0
	v_lshl_add_u64 v[154:155], v[140:141], 0, vcc
	global_load_dwordx4 v[100:103], v[154:155], off
	s_add_u32 vcc_lo, s30, 0x53322000
	s_addc_u32 vcc_hi, s31, 0
	v_lshl_add_u64 v[154:155], v[140:141], 0, vcc
	global_load_dwordx4 v[104:107], v[154:155], off
	s_add_u32 vcc_lo, s30, 0x532c1000
	s_addc_u32 vcc_hi, s31, 0
	v_lshl_add_u64 v[154:155], v[140:141], 0, vcc
	global_load_dwordx4 v[108:111], v[154:155], off
	s_add_u32 vcc_lo, s30, 0x53321000
	s_addc_u32 vcc_hi, s31, 0
	v_lshl_add_u64 v[154:155], v[140:141], 0, vcc
	global_load_dwordx4 v[112:115], v[154:155], off
	s_waitcnt lgkmcnt(0)
	v_mfma_f32_32x32x16_bf16 v[84:99], v[198:201], v[146:149], v[84:99]
	ds_read_b128 v[146:149], v138 offset:32768
	ds_read_b128 v[198:201], v138 offset:40960
	v_and_b32_e32 v138, 64, v215
	v_add_u32_e32 v138, 64, v138
	s_waitcnt vmcnt(5) lgkmcnt(1)
	v_mfma_f32_32x32x16_bf16 v[68:83], v[146:149], v[150:153], v[68:83]
	ds_read_b128 v[146:149], v2 offset:32768
	s_waitcnt lgkmcnt(1)
	v_mfma_f32_32x32x16_bf16 v[84:99], v[198:201], v[150:153], v[84:99]
	ds_read_b128 v[150:153], v2 offset:40960
	v_xor_b32_e32 v2, 32, v215
	v_cmp_lt_i32_e32 vcc, v2, v138
	s_nop 1
	v_cndmask_b32_e32 v2, v215, v2, vcc
	v_lshlrev_b32_e32 v138, 2, v2
	v_cmp_lt_i32_e32 vcc, s4, v165
	s_waitcnt vmcnt(4) lgkmcnt(0)
	v_mfma_f32_32x32x16_bf16 v[84:99], v[150:153], v[142:145], v[84:99]
	s_nop 11
	v_mul_f32_e32 v198, 0x3e0293ee, v86
	v_mfma_f32_32x32x16_bf16 v[68:83], v[146:149], v[142:145], v[68:83]
	v_mul_f32_e32 v206, 0x3e0293ee, v94
	v_mul_f32_e32 v181, 0x3e0293ee, v84
	v_mul_f32_e32 v199, 0x3e0293ee, v87
	v_mul_f32_e32 v207, 0x3e0293ee, v95
	v_mul_f32_e32 v222, 0x3e0293ee, v98
	v_exp_f32_e64 v84, -|v198|
	v_exp_f32_e64 v143, -|v206|
	v_mul_f32_e32 v221, 0x3e0293ee, v97
	v_exp_f32_e64 v86, -|v199|
	v_exp_f32_e64 v145, -|v207|
	v_exp_f32_e64 v151, -|v222|
	v_exp_f32_e64 v149, -|v221|
	v_mul_f32_e32 v204, 0x3e0293ee, v92
	v_mul_f32_e32 v200, 0x3e0293ee, v88
	v_mul_f32_e32 v220, 0x3e0293ee, v96
	v_mul_f32_e32 v2, 0x3e0293ee, v68
	v_mul_f32_e32 v179, 0x3e0293ee, v69
	v_exp_f32_e64 v68, -|v181|
	v_exp_f32_e64 v98, -|v204|
	v_add_f32_e32 v84, 1.0, v84
	v_add_f32_e32 v196, 1.0, v143
	v_mul_f32_e32 v180, 0x3e0293ee, v70
	v_exp_f32_e64 v88, -|v200|
	v_exp_f32_e64 v147, -|v220|
	v_exp_f32_e64 v155, -|v2|
	v_exp_f32_e64 v185, -|v179|
	v_add_f32_e32 v86, 1.0, v86
	v_add_f32_e32 v197, 1.0, v145
	v_add_f32_e32 v227, 1.0, v151
	v_log_f32_e32 v151, v84
	v_log_f32_e32 v84, v196
	v_exp_f32_e64 v186, -|v180|
	v_add_f32_e32 v226, 1.0, v149
	v_log_f32_e32 v149, v86
	v_log_f32_e32 v86, v197
	v_mul_f32_e32 v183, 0x3e0293ee, v85
	v_mul_f32_e32 v205, 0x3e0293ee, v93
	v_mul_f32_e32 v203, 0x3e0293ee, v91
	v_mul_f32_e32 v223, 0x3e0293ee, v99
; DEVI void stick_half(f32x16& x, float& carry, bool diag, int kv0, int tq, int hi) {
;     f32x16 lk; const int dq = diag ? tq - kv0 : 64;
; #pragma unroll
;     for (int r = 0; r < 16; ++r) {
;         float z = x[r] * C2;
;         float l = -(fmaxf(z, 0.f) + __builtin_amdgcn_logf(1.f + __builtin_amdgcn_exp2f(-fabsf(z))));
;         if ((r & 3) + 8 * (r >> 2) >= dq) { l = 0.f; z = -INFINITY; }
;         lk[r] = l; x[r] = z;
;     }
	v_exp_f32_e64 v70, -|v183|
	v_exp_f32_e64 v99, -|v205|
	v_max_f32_e32 v144, 0, v206
	v_add_f32_e32 v68, 1.0, v68
	v_add_f32_e32 v98, 1.0, v98
	v_mul_f32_e32 v201, 0x3e0293ee, v89
	v_exp_f32_e64 v94, -|v203|
	v_max_f32_e32 v146, 0, v207
	v_exp_f32_e64 v153, -|v223|
	v_add_f32_e32 v88, 1.0, v88
	v_add_f32_e32 v225, 1.0, v147
	v_add_f32_e32 v229, 1.0, v155
	v_log_f32_e32 v155, v68
	v_log_f32_e32 v68, v98
	v_add_f32_e32 v196, v144, v84
	v_add_f32_e32 v84, 1.0, v185
	v_mul_f32_e32 v202, 0x3e0293ee, v90
	v_exp_f32_e64 v90, -|v201|
	v_log_f32_e32 v147, v88
	v_log_f32_e32 v88, v225
	v_log_f32_e32 v98, v229
	v_add_f32_e32 v197, v146, v86
	v_log_f32_e32 v84, v84
	v_add_f32_e32 v86, 1.0, v186
	v_mul_f32_e32 v225, 0x3e0293ee, v71
	v_log_f32_e32 v86, v86
	v_exp_f32_e64 v71, -|v225|
	v_max_f32_e32 v96, 0, v204
	v_add_f32_e32 v70, 1.0, v70
	v_add_f32_e32 v187, 1.0, v99
	v_max_f32_e32 v184, 0, v2
	v_add_f32_e32 v94, 1.0, v94
	v_add_f32_e32 v228, 1.0, v153
	v_log_f32_e32 v153, v70
	v_log_f32_e32 v70, v187
	v_add_f32_e32 v187, v96, v68
	v_max_f32_e32 v68, 0, v179
	v_add_f32_e32 v90, 1.0, v90
	v_log_f32_e32 v99, v94
	v_log_f32_e32 v94, v228
	v_add_f32_e32 v228, v184, v98
	v_add_f32_e32 v184, v68, v84
	v_max_f32_e32 v68, 0, v180
	v_exp_f32_e64 v92, -|v202|
	v_log_f32_e32 v145, v90
	v_log_f32_e32 v90, v226
	v_add_f32_e32 v185, v68, v86
	v_add_f32_e32 v68, 1.0, v71
	v_mul_f32_e32 v226, 0x3e0293ee, v72
	v_log_f32_e32 v68, v68
	v_exp_f32_e64 v71, -|v226|
	v_add_f32_e32 v92, 1.0, v92
	v_max_f32_e32 v72, 0, v225
	v_max_f32_e32 v154, 0, v223
	v_log_f32_e32 v143, v92
	v_log_f32_e32 v92, v227
	v_add_f32_e32 v186, v72, v68
	v_add_f32_e32 v68, 1.0, v71
	v_mul_f32_e32 v227, 0x3e0293ee, v73
	v_add_f32_e32 v246, v154, v94
	v_log_f32_e32 v154, v68
	v_exp_f32_e64 v68, -|v227|
	v_mul_f32_e32 v229, 0x3e0293ee, v74
	v_exp_f32_e64 v71, -|v229|
	v_max_f32_e32 v152, 0, v222
	v_add_f32_e32 v68, 1.0, v68
	v_max_f32_e32 v150, 0, v221
	v_add_f32_e32 v243, v152, v92
	v_log_f32_e32 v152, v68
	v_add_f32_e32 v68, 1.0, v71
	v_mul_f32_e32 v230, 0x3e0293ee, v75
	v_add_f32_e32 v241, v150, v90
	v_log_f32_e32 v150, v68
	v_exp_f32_e64 v68, -|v230|
	v_mul_f32_e32 v231, 0x3e0293ee, v76
	v_exp_f32_e64 v71, -|v231|
	v_max_f32_e32 v148, 0, v220
	v_add_f32_e32 v68, 1.0, v68
	v_add_f32_e32 v239, v148, v88
	v_log_f32_e32 v148, v68
	v_add_f32_e32 v68, 1.0, v71
	v_mul_f32_e32 v232, 0x3e0293ee, v77
	v_log_f32_e32 v146, v68
	v_exp_f32_e64 v68, -|v232|
	v_mul_f32_e32 v233, 0x3e0293ee, v78
	v_exp_f32_e64 v71, -|v233|
	v_mul_f32_e32 v234, 0x3e0293ee, v79
	v_add_f32_e32 v68, 1.0, v68
	v_log_f32_e32 v144, v68
	v_add_f32_e32 v68, 1.0, v71
	v_exp_f32_e64 v71, -|v234|
	v_mul_f32_e32 v235, 0x3e0293ee, v80
	v_exp_f32_e64 v72, -|v235|
	v_mul_f32_e32 v236, 0x3e0293ee, v81
	v_add_f32_e32 v71, 1.0, v71
	v_log_f32_e32 v98, v71
	v_add_f32_e32 v71, 1.0, v72
	v_exp_f32_e64 v72, -|v236|
	v_log_f32_e32 v71, v71
	v_max_f32_e32 v73, 0, v235
	v_mul_f32_e32 v237, 0x3e0293ee, v82
	v_add_f32_e32 v72, 1.0, v72
	v_add_f32_e32 v247, v73, v71
	v_log_f32_e32 v72, v72
	v_exp_f32_e64 v73, -|v237|
	v_mul_f32_e32 v238, 0x3e0293ee, v83
	v_exp_f32_e64 v74, -|v238|
	v_max_f32_e32 v71, 0, v236
	v_add_f32_e32 v248, v71, v72
	v_add_f32_e32 v71, 1.0, v73
	v_log_f32_e32 v71, v71
	v_add_f32_e32 v72, 1.0, v74
	v_log_f32_e32 v72, v72
	v_max_f32_e32 v73, 0, v237
	v_add_f32_e32 v212, v73, v71
	v_max_f32_e32 v71, 0, v238
	v_add_f32_e32 v208, v71, v72
	v_sub_u32_e32 v72, v1, v224
	v_max_f32_e32 v142, 0, v205
	v_sub_u32_e32 v71, v136, v224
	v_cndmask_b32_e64 v217, v72, 64, vcc
	v_max_f32_e32 v97, 0, v181
	v_max_f32_e32 v95, 0, v183
	v_max_f32_e32 v93, 0, v198
	v_max_f32_e32 v91, 0, v199
	v_add_f32_e32 v70, v142, v70
	v_max_f32_e32 v96, 0, v226
	v_max_f32_e32 v94, 0, v227
	v_max_f32_e32 v92, 0, v229
	v_max_f32_e32 v90, 0, v230
	v_log_f32_e32 v142, v68
	v_cndmask_b32_e64 v218, v71, 64, vcc
	v_cmp_lt_i32_e64 s[52:53], 17, v217
	v_cmp_lt_i32_e64 s[70:71], 0, v217
	v_cmp_lt_i32_e64 s[8:9], 8, v218
	v_cndmask_b32_e64 v242, 0, -v70, s[52:53]
	v_pk_add_f32 v[70:71], v[96:97], v[154:155]
	v_pk_add_f32 v[72:73], v[94:95], v[152:153]
	v_cmp_lt_i32_e64 s[74:75], 1, v217
	v_cmp_lt_i32_e64 s[44:45], 9, v218
	v_pk_add_f32 v[74:75], v[92:93], v[150:151]
	v_cmp_lt_i32_e64 s[76:77], 2, v217
	v_cmp_lt_i32_e64 s[46:47], 10, v218
	v_pk_add_f32 v[76:77], v[90:91], v[148:149]
	v_cmp_lt_i32_e64 s[80:81], 3, v217
	v_cmp_lt_i32_e64 s[48:49], 11, v218
	v_cndmask_b32_e64 v71, 0, -v71, s[70:71]
	v_cndmask_b32_e64 v70, 0, -v70, s[8:9]
	v_cndmask_b32_e64 v73, 0, -v73, s[74:75]
	v_cndmask_b32_e64 v72, 0, -v72, s[44:45]
	v_cndmask_b32_e64 v75, 0, -v75, s[76:77]
	v_cndmask_b32_e64 v74, 0, -v74, s[46:47]
	v_cndmask_b32_e64 v77, 0, -v77, s[80:81]
	v_cndmask_b32_e64 v76, 0, -v76, s[48:49]
	v_max_f32_e32 v89, 0, v200
	v_max_f32_e32 v87, 0, v201
	v_max_f32_e32 v85, 0, v202
	v_max_f32_e32 v69, 0, v203
	v_max_f32_e32 v88, 0, v231
	v_max_f32_e32 v86, 0, v232
	v_max_f32_e32 v84, 0, v233
	v_max_f32_e32 v68, 0, v234
	v_pk_add_f32 v[78:79], v[70:71], v[72:73]
	v_pk_add_f32 v[80:81], v[74:75], v[76:77]
	v_cmp_lt_i32_e64 s[84:85], 8, v217
	v_pk_add_f32 v[94:95], v[78:79], v[80:81]
	v_pk_add_f32 v[78:79], v[88:89], v[146:147]
	v_cmp_lt_i32_e64 s[66:67], 16, v218
	v_pk_add_f32 v[82:83], v[86:87], v[144:145]
	v_cmp_lt_i32_e64 s[90:91], 9, v217
	v_cmp_lt_i32_e64 s[68:69], 17, v218
	v_pk_add_f32 v[84:85], v[84:85], v[142:143]
	v_cmp_lt_i32_e64 s[4:5], 10, v217
	v_cmp_lt_i32_e64 s[72:73], 18, v218
	v_pk_add_f32 v[68:69], v[68:69], v[98:99]
	v_cmp_lt_i32_e64 s[92:93], 11, v217
	v_cmp_lt_i32_e64 s[10:11], 19, v218
	v_cmp_lt_i32_e64 s[58:59], 24, v217
	v_cmp_lt_i32_e64 s[60:61], 25, v217
	v_cmp_lt_i32_e64 s[62:63], 26, v217
; DEVI float xlane32(float v) { return __shfl_xor(v, 32); }
; DEVI void stick_half(f32x16& x, float& carry, bool diag, int kv0, int tq, int hi) {
;     ...
;     float T[4], PT[4], S[4], A[4];
; #pragma unroll
;     for (int g = 0; g < 4; ++g) { T[g] = (lk[4 * g] + lk[4 * g + 1]) + (lk[4 * g + 2] + lk[4 * g + 3]); PT[g] = xlane32(T[g]); S[g] = T[g] + PT[g]; }
;     A[3] = 0.f; A[2] = S[3]; A[1] = A[2] + S[2]; A[0] = A[1] + S[1];
; #pragma unroll
;     for (int g = 0; g < 4; ++g) {
;         const float i3 = (carry + A[g] + (hi == 0 ? PT[g] : 0.f)) + lk[4 * g + 3], i2 = i3 + lk[4 * g + 2], i1 = i2 + lk[4 * g + 1], i0 = i1 + lk[4 * g];
;         x[4 * g + 3] = __builtin_amdgcn_exp2f(x[4 * g + 3] + i3); x[4 * g + 2] = __builtin_amdgcn_exp2f(x[4 * g + 2] + i2);
;         x[4 * g + 1] = __builtin_amdgcn_exp2f(x[4 * g + 1] + i1); x[4 * g] = __builtin_amdgcn_exp2f(x[4 * g] + i0);
;     }
;     carry += A[0] + S[0];
; template <int MODE>
; DEVI void attn_unit(LAS unsigned char* lds, const bf16_t* Qw, int ldq, const bf16_t* Kb, const bf16_t* Vb, int ldk, bf16_t* Ow, int ldo,
;                     int j_first, int ntiles, int jstep, int wj_lo, int wj_hi, int t0) {
;     ...
;                 if (__all(carry < -152.f)) { mydone = true; if (lane == 0) dflag[(i & 1) * 8 + wid] = 1u; }
	v_cmp_lt_i32_e64 s[64:65], 27, v217
	v_cndmask_b32_e64 v79, 0, -v79, s[84:85]
	v_cndmask_b32_e64 v78, 0, -v78, s[66:67]
	v_cndmask_b32_e64 v83, 0, -v83, s[90:91]
	v_cndmask_b32_e64 v82, 0, -v82, s[68:69]
	v_cndmask_b32_e64 v85, 0, -v85, s[4:5]
	v_cndmask_b32_e64 v84, 0, -v84, s[72:73]
	v_cndmask_b32_e64 v89, 0, -v69, s[92:93]
	v_cndmask_b32_e64 v88, 0, -v68, s[10:11]
	v_cmp_lt_i32_e64 s[50:51], 16, v217
	v_cmp_lt_i32_e64 s[54:55], 18, v217
	v_cmp_lt_i32_e64 s[56:57], 19, v217
	v_cndmask_b32_e64 v224, 0, -v239, s[58:59]
	v_cndmask_b32_e64 v239, 0, -v241, s[60:61]
	v_cndmask_b32_e64 v241, 0, -v243, s[62:63]
	v_cndmask_b32_e64 v243, 0, -v246, s[64:65]
	v_pk_add_f32 v[68:69], v[78:79], v[82:83]
	v_pk_add_f32 v[86:87], v[84:85], v[88:89]
	v_cndmask_b32_e64 v240, 0, -v187, s[50:51]
	v_cndmask_b32_e64 v244, 0, -v196, s[54:55]
	v_cndmask_b32_e64 v245, 0, -v197, s[56:57]
	v_pk_add_f32 v[96:97], v[68:69], v[86:87]
	v_cmp_lt_i32_e64 s[78:79], 24, v218
	v_add_f32_e32 v80, v224, v239
	v_add_f32_e32 v86, v241, v243
	v_cmp_lt_i32_e64 s[82:83], 25, v218
	v_add_f32_e32 v69, v240, v242
	v_add_f32_e32 v87, v244, v245
	v_cndmask_b32_e64 v68, 0, -v247, s[78:79]
	v_add_f32_e32 v80, v80, v86
	v_cndmask_b32_e64 v86, 0, -v248, s[82:83]
	v_pk_add_f32 v[98:99], v[68:69], v[86:87]
	ds_bpermute_b32 v143, v138, v99
	ds_bpermute_b32 v147, v138, v80
	v_cmp_lt_i32_e64 s[86:87], 26, v218
	v_cmp_lt_i32_e64 s[88:89], 27, v218
	v_cmp_lt_i32_e64 s[6:7], 0, v218
	v_cndmask_b32_e64 v87, 0, -v212, s[86:87]
	v_cndmask_b32_e64 v146, 0, -v208, s[88:89]
	v_add_f32_e32 v142, v87, v146
	v_cmp_lt_i32_e64 s[94:95], 1, v218
	v_cmp_lt_i32_e64 s[96:97], 2, v218
	v_cmp_lt_i32_e32 vcc, 3, v218
	s_waitcnt lgkmcnt(1)
	v_pk_add_f32 v[98:99], v[98:99], v[142:143]
	v_cndmask_b32_e64 v142, 0, -v228, s[6:7]
	v_cndmask_b32_e64 v148, 0, -v184, s[94:95]
	v_cndmask_b32_e64 v149, 0, -v185, s[96:97]
	v_cndmask_b32_e64 v150, 0, -v186, vcc
	ds_bpermute_b32 v91, v138, v97
	s_waitcnt lgkmcnt(1)
	v_add_f32_e32 v93, v80, v147
	ds_bpermute_b32 v90, v138, v96
	ds_bpermute_b32 v92, v138, v98
	v_add_f32_e32 v69, v142, v148
	v_add_f32_e32 v80, v149, v150
	ds_bpermute_b32 v81, v138, v95
	v_add_f32_e32 v69, v69, v80
	ds_bpermute_b32 v80, v138, v94
	ds_bpermute_b32 v151, v138, v69
	s_waitcnt lgkmcnt(4)
	v_pk_add_f32 v[144:145], v[96:97], v[90:91]
	s_waitcnt lgkmcnt(3)
	v_pk_add_f32 v[96:97], v[98:99], v[92:93]
	s_waitcnt lgkmcnt(1)
	v_pk_add_f32 v[94:95], v[94:95], v[80:81]
	v_pk_add_f32 v[98:99], v[144:145], v[96:97]
	s_waitcnt lgkmcnt(0)
	v_add_f32_e32 v138, v69, v151
	v_pk_add_f32 v[144:145], v[94:95], v[98:99]
	s_nop 0
	v_pk_add_f32 v[94:95], v[138:139], v[144:145]
	s_nop 0
	v_add_f32_e32 v69, v94, v95
	v_cmp_gt_f32_e64 s[12:13], s12, v69
	s_cmp_eq_u64 s[12:13], exec
	s_cselect_b64 s[12:13], -1, 0
	s_xor_b64 s[22:23], s[38:39], -1
	s_and_b64 s[26:27], s[22:23], s[12:13]
	s_and_saveexec_b64 s[22:23], s[26:27]
	v_lshl_add_u32 v94, s25, 5, v163
	s_or_b64 s[12:13], s[12:13], exec
	ds_write_b32 v94, v209
	s_or_b64 exec, exec, s[22:23]
	v_add_f32_e32 v99, v139, v99
	v_cndmask_b32_e64 v81, 0, v81, s[42:43]
	v_add_f32_e32 v81, v81, v99
	v_add_f32_e32 v77, v77, v81
	v_add_f32_e32 v75, v75, v77
	v_add_f32_e32 v73, v73, v75
	v_cndmask_b32_e64 v138, v216, v181, s[70:71]
	v_cndmask_b32_e64 v145, v216, v183, s[74:75]
	v_add_f32_e32 v71, v71, v73
	v_add_f32_e32 v73, v145, v73
	v_add_f32_e32 v71, v138, v71
	v_exp_f32_e32 v145, v73
	v_exp_f32_e32 v138, v71
	v_add_f32_e32 v71, v139, v97
	v_cndmask_b32_e64 v73, 0, v91, s[42:43]
	v_add_f32_e32 v71, v73, v71
	v_cndmask_b32_e64 v152, v216, v198, s[76:77]
	v_cndmask_b32_e64 v183, v216, v203, s[92:93]
	v_add_f32_e32 v71, v89, v71
	v_cndmask_b32_e64 v153, v216, v199, s[80:81]
	v_cndmask_b32_e64 v181, v216, v202, s[4:5]
	v_add_f32_e32 v75, v152, v75
	v_add_f32_e32 v73, v85, v71
	v_add_f32_e32 v71, v183, v71
	v_cndmask_b32_e64 v155, v216, v201, s[90:91]
	v_add_f32_e32 v77, v153, v77
	v_exp_f32_e32 v99, v75
	v_add_f32_e32 v75, v83, v73
	v_exp_f32_e32 v83, v71
	v_add_f32_e32 v71, v181, v73
	v_cndmask_b32_e64 v154, v216, v200, s[84:85]
	v_exp_f32_e32 v81, v77
	v_add_f32_e32 v77, v79, v75
	v_exp_f32_e32 v85, v71
	v_add_f32_e32 v71, v155, v75
	v_exp_f32_e32 v89, v71
	v_add_f32_e32 v71, v154, v77
	v_exp_f32_e32 v91, v71
	v_add_f32_e32 v71, v139, v93
	v_cndmask_b32_e64 v73, 0, v143, s[42:43]
	v_add_f32_e32 v71, v73, v71
	v_cndmask_b32_e64 v187, v216, v207, s[56:57]
	v_add_f32_e32 v71, v245, v71
	v_cndmask_b32_e64 v186, v216, v206, s[54:55]
	v_add_f32_e32 v73, v244, v71
	v_add_f32_e32 v71, v187, v71
	v_cndmask_b32_e64 v185, v216, v205, s[52:53]
	v_add_f32_e32 v75, v242, v73
	v_exp_f32_e32 v93, v71
	v_add_f32_e32 v71, v186, v73
	v_cndmask_b32_e64 v184, v216, v204, s[50:51]
	v_add_f32_e32 v77, v240, v75
	v_exp_f32_e32 v97, v71
	v_add_f32_e32 v71, v185, v75
	v_add_f32_e32 v94, 0, v139
	v_exp_f32_e32 v139, v71
	v_add_f32_e32 v71, v184, v77
	v_exp_f32_e32 v143, v71
	v_cndmask_b32_e64 v71, 0, v147, s[42:43]
	v_add_f32_e32 v71, v94, v71
	v_add_f32_e32 v98, v98, v95
	v_cndmask_b32_e64 v80, 0, v80, s[42:43]
	v_cndmask_b32_e64 v199, v216, v223, s[64:65]
	v_add_f32_e32 v71, v243, v71
	v_add_f32_e32 v80, v80, v98
	v_cndmask_b32_e64 v198, v216, v222, s[62:63]
	v_add_f32_e32 v73, v241, v71
	v_add_f32_e32 v71, v199, v71
	v_add_f32_e32 v76, v76, v80
	v_cndmask_b32_e64 v197, v216, v221, s[60:61]
	v_add_f32_e32 v75, v239, v73
	v_exp_f32_e32 v94, v71
	v_add_f32_e32 v71, v198, v73
	v_add_f32_e32 v74, v74, v76
	v_cndmask_b32_e64 v196, v216, v220, s[58:59]
	v_add_f32_e32 v77, v224, v75
	v_exp_f32_e32 v147, v71
	v_add_f32_e32 v71, v197, v75
	v_add_f32_e32 v72, v72, v74
	v_exp_f32_e32 v152, v71
	v_add_f32_e32 v71, v196, v77
; #define FA_SBAR() __builtin_amdgcn_sched_barrier(0)
; template <int D0> DEVI void pv_one(f32x16& od, int vb, bf16x8 pa0, bf16x8 pa1, bf16x8 pa2, bf16x8 pa3) {
;     const s16x4 l0 = tr_read<v_rd_off(D0, 0, 0)>(vb), h0 = tr_read<v_rd_off(D0, 0, 1)>(vb), l1 = tr_read<v_rd_off(D0, 1, 0)>(vb), h1 = tr_read<v_rd_off(D0, 1, 1)>(vb);
;     const s16x4 l2 = tr_read<v_rd_off(D0, 2, 0)>(vb), h2 = tr_read<v_rd_off(D0, 2, 1)>(vb), l3 = tr_read<v_rd_off(D0, 3, 0)>(vb), h3 = tr_read<v_rd_off(D0, 3, 1)>(vb);
;     asm volatile("s_waitcnt lgkmcnt(0)" ::: "memory"); FA_SBAR();
;     ...
;     od = __builtin_amdgcn_mfma_f32_32x32x16_bf16(pa0, FA_PK(l0, h0), od, 0, 0, 0);
;     od = __builtin_amdgcn_mfma_f32_32x32x16_bf16(pa1, FA_PK(l1, h1), od, 0, 0, 0);
;     od = __builtin_amdgcn_mfma_f32_32x32x16_bf16(pa2, FA_PK(l2, h2), od, 0, 0, 0);
;     od = __builtin_amdgcn_mfma_f32_32x32x16_bf16(pa3, FA_PK(l3, h3), od, 0, 0, 0);
;     ...
; }
; DEVI void pv_d0(f32x16* o, int vb, bf16x8 pa0, bf16x8 pa1, bf16x8 pa2, bf16x8 pa3) {
;     pv_one<0>(o[0], vb, pa0, pa1, pa2, pa3); pv_one<1>(o[1], vb, pa0, pa1, pa2, pa3); pv_one<2>(o[2], vb, pa0, pa1, pa2, pa3); pv_one<3>(o[3], vb, pa0, pa1, pa2, pa3);
; }
; DEVI void pack_p(const f32x16& p0, const f32x16& p1, bf16x8& pa0, bf16x8& pa1, bf16x8& pa2, bf16x8& pa3) {
;     ...
;     FA_PK4(p0, 0, pa0); FA_PK4(p0, 8, pa1); FA_PK4(p1, 0, pa2); FA_PK4(p1, 8, pa3);
; DEVI void stick_half(f32x16& x, float& carry, bool diag, int kv0, int tq, int hi) {
;     ...
;         const float i3 = (carry + A[g] + (hi == 0 ? PT[g] : 0.f)) + lk[4 * g + 3], i2 = i3 + lk[4 * g + 2], i1 = i2 + lk[4 * g + 1], i0 = i1 + lk[4 * g];
;         x[4 * g + 3] = __builtin_amdgcn_exp2f(x[4 * g + 3] + i3); x[4 * g + 2] = __builtin_amdgcn_exp2f(x[4 * g + 2] + i2);
;         x[4 * g + 1] = __builtin_amdgcn_exp2f(x[4 * g + 1] + i1); x[4 * g] = __builtin_amdgcn_exp2f(x[4 * g] + i0);
;     }
;     carry += A[0] + S[0];
; template <int MODE>
; DEVI void attn_unit(LAS unsigned char* lds, const bf16_t* Qw, int ldq, const bf16_t* Kb, const bf16_t* Vb, int ldk, bf16_t* Ow, int ldo,
;                     int j_first, int ntiles, int jstep, int wj_lo, int wj_hi, int t0) {
;     ...
;                 if (__all(carry < -152.f)) { mydone = true; if (lane == 0) dflag[(i & 1) * 8 + wid] = 1u; }
;                 pack_p(p0, p1, pa0, pa1, pa2, pa3);
;     ...
;             pv_d0(o, vb0 + buf * SHM_V, pa0, pa1, pa2, pa3);
	v_cndmask_b32_e64 v77, v216, v226, s[8:9]
	v_add_f32_e32 v70, v70, v72
	v_cndmask_b32_e64 v79, v216, v227, s[44:45]
	v_add_f32_e32 v70, v77, v70
	v_add_f32_e32 v72, v79, v72
	v_exp_f32_e32 v77, v70
	v_add_f32_e32 v70, v96, v95
	v_cndmask_b32_e64 v79, 0, v90, s[42:43]
	v_add_f32_e32 v70, v79, v70
	v_cndmask_b32_e64 v183, v216, v234, s[10:11]
	v_add_f32_e32 v70, v88, v70
	v_cndmask_b32_e64 v181, v216, v233, s[72:73]
	v_add_f32_e32 v79, v84, v70
	v_add_f32_e32 v70, v183, v70
	v_cndmask_b32_e64 v73, v216, v180, s[96:97]
	v_cndmask_b32_e64 v180, v216, v232, s[68:69]
	v_add_f32_e32 v80, v82, v79
	v_exp_f32_e32 v82, v70
	v_add_f32_e32 v70, v181, v79
	v_exp_f32_e32 v153, v71
	v_cndmask_b32_e64 v71, v216, v179, s[94:95]
	v_cndmask_b32_e64 v179, v216, v231, s[66:67]
	v_add_f32_e32 v78, v78, v80
	v_exp_f32_e32 v79, v70
	v_add_f32_e32 v70, v180, v80
	v_add_f32_e32 v144, v144, v95
	v_cndmask_b32_e64 v151, 0, v151, s[42:43]
	v_exp_f32_e32 v80, v70
	v_add_f32_e32 v70, v179, v78
	v_add_f32_e32 v144, v151, v144
	v_exp_f32_e32 v78, v70
	v_add_f32_e32 v70, 0, v95
	v_cndmask_b32_e64 v84, 0, v92, s[42:43]
	v_add_f32_e32 v144, v150, v144
	v_add_f32_e32 v70, v84, v70
	v_cndmask_b32_e64 v187, v216, v238, s[88:89]
	v_add_f32_e32 v149, v149, v144
	v_add_f32_e32 v70, v146, v70
	v_cndmask_b32_e64 v186, v216, v237, s[86:87]
	v_add_f32_e32 v148, v148, v149
	v_add_f32_e32 v84, v87, v70
	v_add_f32_e32 v70, v187, v70
	v_cndmask_b32_e64 v2, v216, v2, s[6:7]
	v_cndmask_b32_e32 v75, v216, v225, vcc
	v_cndmask_b32_e64 v154, v216, v229, s[46:47]
	v_cndmask_b32_e64 v155, v216, v230, s[48:49]
	v_cndmask_b32_e64 v185, v216, v236, s[82:83]
	v_add_f32_e32 v142, v142, v148
	v_add_f32_e32 v86, v86, v84
	v_exp_f32_e32 v87, v70
	v_add_f32_e32 v70, v186, v84
	v_cndmask_b32_e64 v184, v216, v235, s[78:79]
	v_add_f32_e32 v75, v75, v144
	v_add_f32_e32 v73, v73, v149
	v_add_f32_e32 v71, v71, v148
	v_add_f32_e32 v2, v2, v142
	v_add_f32_e32 v76, v155, v76
	v_add_f32_e32 v74, v154, v74
	v_add_f32_e32 v68, v68, v86
	v_exp_f32_e32 v84, v70
	v_add_f32_e32 v70, v185, v86
	v_exp_f32_e32 v75, v75
	v_exp_f32_e32 v73, v73
	v_exp_f32_e32 v71, v71
	v_exp_f32_e32 v2, v2
	v_exp_f32_e32 v76, v76
	v_exp_f32_e32 v74, v74
	v_exp_f32_e32 v72, v72
	v_exp_f32_e32 v86, v70
	v_add_f32_e32 v68, v184, v68
	v_exp_f32_e32 v68, v68
	v_cvt_pk_bf16_f32 v70, v2, v71
	v_cvt_pk_bf16_f32 v71, v73, v75
	v_cvt_pk_bf16_f32 v72, v77, v72
	v_cvt_pk_bf16_f32 v73, v74, v76
	v_cvt_pk_bf16_f32 v74, v78, v80
	v_cvt_pk_bf16_f32 v75, v79, v82
	v_cvt_pk_bf16_f32 v76, v68, v86
	v_cvt_pk_bf16_f32 v77, v84, v87
	v_cvt_pk_bf16_f32 v78, v138, v145
	v_cvt_pk_bf16_f32 v79, v99, v81
	v_cvt_pk_bf16_f32 v80, v91, v89
	v_cvt_pk_bf16_f32 v81, v85, v83
	v_cvt_pk_bf16_f32 v82, v143, v139
	v_cvt_pk_bf16_f32 v83, v97, v93
	v_cvt_pk_bf16_f32 v84, v153, v152
	v_cvt_pk_bf16_f32 v85, v147, v94
	v_add_u32_e32 v2, s1, v177
	ds_read_b64_tr_b16 v[86:87], v2 offset:0
	ds_read_b64_tr_b16 v[88:89], v2 offset:0x800
	ds_read_b64_tr_b16 v[90:91], v2 offset:0x1000
	ds_read_b64_tr_b16 v[92:93], v2 offset:0x1800
	ds_read_b64_tr_b16 v[94:95], v2 offset:0x2000
	ds_read_b64_tr_b16 v[96:97], v2 offset:0x2800
	ds_read_b64_tr_b16 v[142:143], v2 offset:0x3000
	ds_read_b64_tr_b16 v[144:145], v2 offset:0x3800
	s_waitcnt lgkmcnt(0)
	v_permlane32_swap_b32_e32 v70, v72
	v_permlane32_swap_b32_e32 v71, v73
	v_permlane32_swap_b32_e32 v74, v76
	v_permlane32_swap_b32_e32 v75, v77
	v_permlane32_swap_b32_e32 v78, v80
	v_permlane32_swap_b32_e32 v79, v81
	v_permlane32_swap_b32_e32 v82, v84
	v_permlane32_swap_b32_e32 v83, v85
	v_mfma_f32_32x32x16_bf16 v[4:19], v[70:73], v[86:89], v[4:19]
	ds_read_b64_tr_b16 v[86:87], v2 offset:0x200
	ds_read_b64_tr_b16 v[88:89], v2 offset:0xa00
	v_mfma_f32_32x32x16_bf16 v[4:19], v[74:77], v[90:93], v[4:19]
	ds_read_b64_tr_b16 v[90:91], v2 offset:0x1200
	ds_read_b64_tr_b16 v[92:93], v2 offset:0x1a00
	v_mfma_f32_32x32x16_bf16 v[4:19], v[78:81], v[94:97], v[4:19]
	ds_read_b64_tr_b16 v[94:95], v2 offset:0x2200
	ds_read_b64_tr_b16 v[96:97], v2 offset:0x2a00
	v_mfma_f32_32x32x16_bf16 v[4:19], v[82:85], v[142:145], v[4:19]
	ds_read_b64_tr_b16 v[142:143], v2 offset:0x3200
	ds_read_b64_tr_b16 v[144:145], v2 offset:0x3a00
	s_waitcnt lgkmcnt(0)
	v_mfma_f32_32x32x16_bf16 v[20:35], v[70:73], v[86:89], v[20:35]
	ds_read_b64_tr_b16 v[86:87], v2 offset:0x400
	ds_read_b64_tr_b16 v[88:89], v2 offset:0xc00
	v_mfma_f32_32x32x16_bf16 v[20:35], v[74:77], v[90:93], v[20:35]
	ds_read_b64_tr_b16 v[90:91], v2 offset:0x1400
	ds_read_b64_tr_b16 v[92:93], v2 offset:0x1c00
	v_mfma_f32_32x32x16_bf16 v[20:35], v[78:81], v[94:97], v[20:35]
	ds_read_b64_tr_b16 v[94:95], v2 offset:0x2400
	ds_read_b64_tr_b16 v[96:97], v2 offset:0x2c00
	v_mfma_f32_32x32x16_bf16 v[20:35], v[82:85], v[142:145], v[20:35]
	ds_read_b64_tr_b16 v[142:143], v2 offset:0x3400
	ds_read_b64_tr_b16 v[144:145], v2 offset:0x3c00
	s_waitcnt lgkmcnt(0)
	v_mfma_f32_32x32x16_bf16 v[36:51], v[70:73], v[86:89], v[36:51]
	ds_read_b64_tr_b16 v[86:87], v2 offset:0x600
	ds_read_b64_tr_b16 v[88:89], v2 offset:0xe00
	v_mfma_f32_32x32x16_bf16 v[36:51], v[74:77], v[90:93], v[36:51]
	ds_read_b64_tr_b16 v[90:91], v2 offset:0x1600
	ds_read_b64_tr_b16 v[92:93], v2 offset:0x1e00
	v_mfma_f32_32x32x16_bf16 v[36:51], v[78:81], v[94:97], v[36:51]
	ds_read_b64_tr_b16 v[94:95], v2 offset:0x2600
	ds_read_b64_tr_b16 v[96:97], v2 offset:0x2e00
	v_mfma_f32_32x32x16_bf16 v[36:51], v[82:85], v[142:145], v[36:51]
	ds_read_b64_tr_b16 v[142:143], v2 offset:0x3600
	ds_read_b64_tr_b16 v[144:145], v2 offset:0x3e00
	s_waitcnt lgkmcnt(0)
	v_mfma_f32_32x32x16_bf16 v[52:67], v[70:73], v[86:89], v[52:67]
	s_andn2_b64 s[4:5], s[14:15], exec
	s_and_b64 s[6:7], s[12:13], exec
	s_or_b64 s[14:15], s[4:5], s[6:7]
	v_mov_b32_e32 v139, v69
	v_mfma_f32_32x32x16_bf16 v[52:67], v[74:77], v[90:93], v[52:67]
	v_mfma_f32_32x32x16_bf16 v[52:67], v[78:81], v[94:97], v[52:67]
	v_mfma_f32_32x32x16_bf16 v[52:67], v[82:85], v[142:145], v[52:67]
